# DSA tile loop: waves 4-7 delayed by s_sleep 10 after each tile barrier (half-block stagger), on top of band-unit rebalancing
# baseline (speedup 1.0000x reference)
; template <int MODE>
; DEVI void attn_unit(LAS unsigned char* lds, const bf16_t* Qw, int ldq, const bf16_t* Kb, const bf16_t* Vb, int ldk, bf16_t* Ow, int ldo,
;                     int j_first, int ntiles, int jstep, int wj_lo, int wj_hi, int t0) {
;     ...
;         asm volatile("s_waitcnt lgkmcnt(0)" ::: "memory"); __builtin_amdgcn_s_barrier(); asm volatile("" ::: "memory");
;         if constexpr (MODE == M_STICK) {
;             if (i > 0) { const u32x4 f0 = *(LAS const u32x4*)(dflag + ((i - 1) & 1) * 8), f1 = *(LAS const u32x4*)(dflag + ((i - 1) & 1) * 8 + 4);
;                 if ((f0.x & f0.y & f0.z & f0.w & f1.x & f1.y & f1.z & f1.w) != 0u) break; }
;             if (lane == 0) dflag[(i & 1) * 8 + wid] = mydone ? 1u : 0u;
;         }
;         if (j >= wj_lo && j <= wj_hi && !mydone) {
;             f32x16 p0, p1;
;             if constexpr (MODE == M_STICK) {
;                 int qz_ = 0; asm volatile("" : "+v"(qz_)); const bf16_t* qp2 = qp + qz_;
; #pragma unroll
;                 for (int d0 = 0; d0 < 8; ++d0) qr[d0] = *(const bf16x8*)(qp2 + d0 * 16); }
;             qkt(p0, p1, K_lds + buf * SHM_K, qr, r32, hi);
;             bf16x8 pa0, pa1, pa2, pa3;
;             if constexpr (MODE == M_STICK) {
;                 const int tq = t0 + r32; const bool diag = (64 * j + 63 >= t0);
;                 stick_half(p1, carry, diag, 64 * j + 32 + 4 * hi, tq, hi);
;                 stick_half(p0, carry, diag, 64 * j + 4 * hi, tq, hi);
;                 if (__all(carry < -152.f)) { mydone = true; if (lane == 0) dflag[(i & 1) * 8 + wid] = 1u; }
;                 pack_p(p0, p1, pa0, pa1, pa2, pa3);
;             } else {
;                 if constexpr (MODE == M_BAND) {
;                     const int cw = t0 >> 6;
;                     if (j <= cw - 3) { const float bc = bias2[191];
; #pragma unroll
;                         for (int r = 0; r < 16; ++r) { p0[r] = fmaf(p0[r], C2, bc); p1[r] = fmaf(p1[r], C2, bc); }
;                     } else { const int d0 = (t0 + r32) - (64 * j + 4 * hi) + 63;
; #pragma unroll
;                         for (int r = 0; r < 16; ++r) { const int da = d0 - ((r & 3) + 8 * (r >> 2)); const int ia = da > 191 ? 191 : da; const int db = da - 32; const int ib = db > 191 ? 191 : db;
;                             p0[r] = fmaf(p0[r], C2, bias2[ia]); p1[r] = fmaf(p1[r], C2, bias2[ib]); } }
;                 }
.LBB11_1656:
	v_add_u32_e32 v184, s4, v175
	s_waitcnt lgkmcnt(0)
	s_barrier
	v_readlane_b32 s101, v249, 40
	s_cmp_lt_u32 s101, 4
	s_cbranch_scc1 .Lstg_dsa
	s_sleep 10
.Lstg_dsa:
	v_and_b32_e32 v186, 64, v215
	v_add_u32_e32 v186, 64, v186
	s_mov_b32 s4, 0x41000000
	v_add_u32_e32 v185, v184, v176
	ds_read_b128 v[220:223], v185 offset:32768
	ds_read_b128 v[224:227], v185 offset:40960
	v_add_u32_e32 v236, v184, v177
	ds_read_b128 v[228:231], v236 offset:32768
	ds_read_b128 v[232:235], v236 offset:40960
	s_waitcnt lgkmcnt(3)
	v_mfma_f32_32x32x16_bf16 v[68:83], v[220:223], v[100:103], 0
	v_add_u32_e32 v237, v184, v178
	ds_read_b128 v[220:223], v237 offset:32768
	s_waitcnt lgkmcnt(3)
	v_mfma_f32_32x32x16_bf16 v[84:99], v[224:227], v[100:103], 0
	ds_read_b128 v[224:227], v237 offset:40960
	s_waitcnt lgkmcnt(3)
	v_mfma_f32_32x32x16_bf16 v[68:83], v[228:231], v[104:107], v[68:83]
	v_add_u32_e32 v238, v184, v179
	ds_read_b128 v[228:231], v238 offset:32768
	s_waitcnt lgkmcnt(3)
	v_mfma_f32_32x32x16_bf16 v[84:99], v[232:235], v[104:107], v[84:99]
	ds_read_b128 v[232:235], v238 offset:40960
	s_waitcnt lgkmcnt(3)
	v_mfma_f32_32x32x16_bf16 v[68:83], v[220:223], v[108:111], v[68:83]
	v_add_u32_e32 v185, v184, v181
	ds_read_b128 v[220:223], v185 offset:32768
	s_waitcnt lgkmcnt(3)
	v_mfma_f32_32x32x16_bf16 v[84:99], v[224:227], v[108:111], v[84:99]
	ds_read_b128 v[224:227], v185 offset:40960
	s_waitcnt lgkmcnt(3)
	v_mfma_f32_32x32x16_bf16 v[68:83], v[228:231], v[112:115], v[68:83]
	v_add_u32_e32 v236, v184, v183
	ds_read_b128 v[228:231], v236 offset:32768
	s_waitcnt lgkmcnt(3)
	v_mfma_f32_32x32x16_bf16 v[84:99], v[232:235], v[112:115], v[84:99]
	ds_read_b128 v[232:235], v236 offset:40960
	s_waitcnt lgkmcnt(3)
	v_mfma_f32_32x32x16_bf16 v[68:83], v[220:223], v[116:119], v[68:83]
	v_add_u32_e32 v237, v184, v198
	ds_read_b128 v[220:223], v237 offset:32768
	s_waitcnt lgkmcnt(3)
	v_mfma_f32_32x32x16_bf16 v[84:99], v[224:227], v[116:119], v[84:99]
	ds_read_b128 v[224:227], v237 offset:40960
	s_waitcnt lgkmcnt(3)
	v_mfma_f32_32x32x16_bf16 v[68:83], v[228:231], v[120:123], v[68:83]
	v_add_u32_e32 v238, v184, v199
	ds_read_b128 v[228:231], v238 offset:40960
	s_waitcnt lgkmcnt(3)
	v_mfma_f32_32x32x16_bf16 v[84:99], v[232:235], v[120:123], v[84:99]
	ds_read_b128 v[232:235], v238 offset:32768
	s_waitcnt lgkmcnt(3)
	v_mfma_f32_32x32x16_bf16 v[68:83], v[220:223], v[124:127], v[68:83]
	s_waitcnt lgkmcnt(2)
	v_mfma_f32_32x32x16_bf16 v[84:99], v[224:227], v[124:127], v[84:99]
	s_waitcnt lgkmcnt(1)
	v_mfma_f32_32x32x16_bf16 v[84:99], v[228:231], v[128:131], v[84:99]
	s_waitcnt lgkmcnt(0)
	v_mfma_f32_32x32x16_bf16 v[68:83], v[232:235], v[128:131], v[68:83]
	s_nop 8
	v_max_f32_e32 v184, v84, v84
	s_nop 1
	v_max_f32_e32 v185, v68, v68
	v_max_f32_e32 v184, v185, v184
	v_max3_f32 v184, v184, v69, v70
	v_xor_b32_e32 v185, 32, v215
	v_max3_f32 v184, v184, v71, v72
	v_cmp_lt_i32_e32 vcc, v185, v186
	v_max3_f32 v184, v184, v73, v74
	s_nop 0
	v_max3_f32 v184, v184, v75, v76
	s_nop 0
	v_max3_f32 v184, v184, v77, v78
	v_cndmask_b32_e32 v185, v215, v185, vcc
	v_max3_f32 v184, v184, v79, v80
	v_lshlrev_b32_e32 v204, 2, v185
	v_max3_f32 v184, v184, v81, v82
	s_nop 0
	v_max3_f32 v184, v184, v85, v86
	s_nop 0
	v_max3_f32 v184, v184, v87, v88
	s_nop 0
	v_max3_f32 v184, v184, v89, v90
	s_nop 0
	v_max3_f32 v184, v184, v91, v92
	s_nop 0
	v_max3_f32 v184, v184, v93, v94
	s_nop 0
	v_max3_f32 v184, v184, v95, v96
	s_nop 0
	v_max3_f32 v184, v184, v97, v98
	s_nop 0
	v_max3_f32 v184, v184, v83, v99
	ds_bpermute_b32 v185, v204, v184
	v_max_f32_e32 v184, v184, v184
	s_waitcnt lgkmcnt(0)
	v_max_f32_e32 v185, v185, v185
	v_max_f32_e32 v205, v184, v185
	v_fma_f32 v184, v205, s0, -v206
	v_cmp_ge_f32_e32 vcc, s4, v184
	s_cmp_eq_u64 vcc, exec
	s_cbranch_scc1 .LBB11_1660
	v_mul_f32_e32 v184, 0x3e0293ee, v205
	v_max_f32_e32 v184, v184, v184
	v_max_f32_e32 v185, v206, v206
	v_max_f32_e32 v205, v185, v184
	v_sub_f32_e32 v184, v206, v205
	v_exp_f32_e32 v206, v184
	s_and_saveexec_b64 s[4:5], s[40:41]
	ds_write_b32 v180, v206 offset:128
	s_or_b64 exec, exec, s[4:5]
	s_waitcnt lgkmcnt(0)
	v_add_u32_e32 v184, v167, v162
	ds_read_b128 v[220:223], v184 offset:128
	ds_read_b128 v[224:227], v184 offset:160
	ds_read_b128 v[228:231], v184 offset:192
	ds_read_b128 v[232:235], v184 offset:224
	v_mul_f32_e32 v203, v203, v206
	s_waitcnt lgkmcnt(3)
	v_pk_mul_f32 v[6:7], v[6:7], v[222:223]
	s_waitcnt lgkmcnt(2)
	v_pk_mul_f32 v[8:9], v[8:9], v[224:225]
	s_waitcnt lgkmcnt(1)
	v_pk_mul_f32 v[12:13], v[12:13], v[228:229]
	s_waitcnt lgkmcnt(0)
	v_pk_mul_f32 v[16:17], v[16:17], v[232:233]
	v_pk_mul_f32 v[18:19], v[18:19], v[234:235]
	v_pk_mul_f32 v[14:15], v[14:15], v[230:231]
	v_pk_mul_f32 v[10:11], v[10:11], v[226:227]
	v_pk_mul_f32 v[4:5], v[4:5], v[220:221]
	v_pk_mul_f32 v[64:65], v[64:65], v[232:233]
	v_pk_mul_f32 v[60:61], v[60:61], v[228:229]
	v_pk_mul_f32 v[56:57], v[56:57], v[224:225]
	v_pk_mul_f32 v[66:67], v[66:67], v[234:235]
	v_pk_mul_f32 v[62:63], v[62:63], v[230:231]
	v_pk_mul_f32 v[58:59], v[58:59], v[226:227]
	v_pk_mul_f32 v[54:55], v[54:55], v[222:223]
	v_pk_mul_f32 v[52:53], v[52:53], v[220:221]
	v_pk_mul_f32 v[48:49], v[48:49], v[232:233]
	v_pk_mul_f32 v[44:45], v[44:45], v[228:229]
	v_pk_mul_f32 v[40:41], v[40:41], v[224:225]
	v_pk_mul_f32 v[50:51], v[50:51], v[234:235]
	v_pk_mul_f32 v[46:47], v[46:47], v[230:231]
	v_pk_mul_f32 v[42:43], v[42:43], v[226:227]
	v_pk_mul_f32 v[38:39], v[38:39], v[222:223]
	v_pk_mul_f32 v[36:37], v[36:37], v[220:221]
	v_pk_mul_f32 v[32:33], v[32:33], v[232:233]
	v_pk_mul_f32 v[28:29], v[28:29], v[228:229]
	v_pk_mul_f32 v[24:25], v[24:25], v[224:225]
	v_pk_mul_f32 v[34:35], v[34:35], v[234:235]
	v_pk_mul_f32 v[30:31], v[30:31], v[230:231]
	v_pk_mul_f32 v[26:27], v[26:27], v[226:227]
	v_pk_mul_f32 v[22:23], v[22:23], v[222:223]
	v_pk_mul_f32 v[20:21], v[20:21], v[220:221]
	s_branch .LBB11_1661
